# same as the hand-scheduled SWIGLU epilogue version, with two instructions reordered so a v_cndmask reads vcc at least 2 wait states after the v_cmp that wrote it
# baseline (speedup 1.0000x reference)
.LBB0_824:
	s_add_i32 s7, 0, 0x10000
	v_add_u32_e32 v145, s7, v153
	ds_read_b128 v[162:165], v145
	ds_read_b128 v[166:169], v145 offset:1024
	ds_read_b128 v[170:173], v145 offset:2048
	ds_read_b128 v[174:177], v145 offset:3072
	s_add_i32 s6, s0, 2
	s_cmp_eq_u32 s44, s0
	v_lshl_add_u64 v[150:151], v[148:149], 0, s[84:85]
	s_cselect_b64 vcc, -1, 0
	s_cselect_b32 s0, s22, s4
	v_cndmask_b32_e32 v151, v151, v147, vcc
	v_cndmask_b32_e32 v150, v150, v146, vcc
	s_cselect_b32 s1, s23, s5
	v_lshl_add_u64 v[210:211], v[148:149], 0, v[140:141]
	s_add_i32 m0, s28, 0xc000
	ds_read_b128 v[178:181], v157
	ds_read_b128 v[182:185], v157 offset:1024
	ds_read_b128 v[186:189], v157 offset:2048
	ds_read_b128 v[190:193], v157 offset:3072
	ds_read_b128 v[194:197], v157 offset:4096
	ds_read_b128 v[198:201], v157 offset:5120
	ds_read_b128 v[202:205], v157 offset:6144
	ds_read_b128 v[206:209], v157 offset:7168
	global_load_lds_dwordx4 v[210:211], off
	v_lshl_add_u64 v[210:211], v[148:149], 0, v[142:143]
	s_add_i32 m0, s28, 0xe000
	s_nop 0
	global_load_lds_dwordx4 v[210:211], off
	s_waitcnt lgkmcnt(8)
	s_barrier
	s_waitcnt lgkmcnt(0)
	s_waitcnt lgkmcnt(0)
	v_mfma_f32_16x16x32_bf16 v[126:129], v[162:165], v[178:181], v[126:129]
	v_mfma_f32_16x16x32_bf16 v[118:121], v[170:173], v[178:181], v[118:121]
	v_mfma_f32_16x16x32_bf16 v[110:113], v[162:165], v[186:189], v[110:113]
	v_mfma_f32_16x16x32_bf16 v[102:105], v[170:173], v[186:189], v[102:105]
	v_mfma_f32_16x16x32_bf16 v[94:97], v[162:165], v[194:197], v[94:97]
	v_mfma_f32_16x16x32_bf16 v[86:89], v[170:173], v[194:197], v[86:89]
	v_mfma_f32_16x16x32_bf16 v[78:81], v[162:165], v[202:205], v[78:81]
	v_mfma_f32_16x16x32_bf16 v[70:73], v[170:173], v[202:205], v[70:73]
	v_mfma_f32_16x16x32_bf16 v[126:129], v[166:169], v[182:185], v[126:129]
	v_mfma_f32_16x16x32_bf16 v[118:121], v[174:177], v[182:185], v[118:121]
	v_mfma_f32_16x16x32_bf16 v[110:113], v[166:169], v[190:193], v[110:113]
	v_mfma_f32_16x16x32_bf16 v[102:105], v[174:177], v[190:193], v[102:105]
	v_mfma_f32_16x16x32_bf16 v[94:97], v[166:169], v[198:201], v[94:97]
	v_mfma_f32_16x16x32_bf16 v[86:89], v[174:177], v[198:201], v[86:89]
	v_mfma_f32_16x16x32_bf16 v[78:81], v[166:169], v[206:209], v[78:81]
	v_mfma_f32_16x16x32_bf16 v[70:73], v[174:177], v[206:209], v[70:73]
	s_barrier
	s_add_i32 s40, 0, 0x14000
	s_add_i32 s7, s7, s3
	v_add_u32_e32 v145, s40, v153
	v_lshl_add_u64 v[218:219], s[0:1], 0, v[134:135]
	s_mov_b32 m0, s7
	ds_read_b128 v[210:213], v145
	ds_read_b128 v[214:217], v145 offset:1024
	ds_read_b128 v[238:241], v145 offset:2048
	ds_read_b128 v[242:245], v145 offset:3072
	global_load_lds_dwordx4 v[218:219], off
	v_lshl_add_u64 v[224:225], s[0:1], 0, v[130:131]
	s_add_i32 m0, s7, 0x2000
	s_nop 0
	global_load_lds_dwordx4 v[224:225], off
	s_barrier
	s_waitcnt lgkmcnt(0)
	s_waitcnt lgkmcnt(0)
	v_mfma_f32_16x16x32_bf16 v[122:125], v[210:213], v[178:181], v[122:125]
	v_mfma_f32_16x16x32_bf16 v[114:117], v[238:241], v[178:181], v[114:117]
	v_mfma_f32_16x16x32_bf16 v[106:109], v[210:213], v[186:189], v[106:109]
	v_mfma_f32_16x16x32_bf16 v[98:101], v[238:241], v[186:189], v[98:101]
	v_mfma_f32_16x16x32_bf16 v[90:93], v[210:213], v[194:197], v[90:93]
	v_mfma_f32_16x16x32_bf16 v[82:85], v[238:241], v[194:197], v[82:85]
	v_mfma_f32_16x16x32_bf16 v[74:77], v[210:213], v[202:205], v[74:77]
	v_mfma_f32_16x16x32_bf16 v[66:69], v[238:241], v[202:205], v[66:69]
	v_mfma_f32_16x16x32_bf16 v[122:125], v[214:217], v[182:185], v[122:125]
	v_mfma_f32_16x16x32_bf16 v[114:117], v[242:245], v[182:185], v[114:117]
	v_mfma_f32_16x16x32_bf16 v[106:109], v[214:217], v[190:193], v[106:109]
	v_mfma_f32_16x16x32_bf16 v[98:101], v[242:245], v[190:193], v[98:101]
	v_mfma_f32_16x16x32_bf16 v[90:93], v[214:217], v[198:201], v[90:93]
	v_mfma_f32_16x16x32_bf16 v[82:85], v[242:245], v[198:201], v[82:85]
	v_mfma_f32_16x16x32_bf16 v[74:77], v[214:217], v[206:209], v[74:77]
	v_mfma_f32_16x16x32_bf16 v[66:69], v[242:245], v[206:209], v[66:69]
	s_mov_b32 m0, s28
	v_lshl_add_u64 v[230:231], v[150:151], 0, v[136:137]
	s_barrier
	ds_read_b128 v[178:181], v157 offset:16384
	ds_read_b128 v[182:185], v157 offset:17408
	ds_read_b128 v[186:189], v157 offset:18432
	ds_read_b128 v[190:193], v157 offset:19456
	ds_read_b128 v[194:197], v157 offset:20480
	ds_read_b128 v[198:201], v157 offset:21504
	ds_read_b128 v[202:205], v157 offset:22528
	ds_read_b128 v[206:209], v157 offset:23552
	global_load_lds_dwordx4 v[230:231], off
	v_lshl_add_u64 v[246:247], v[150:151], 0, v[132:133]
	s_mov_b32 m0, s29
	s_nop 0
	global_load_lds_dwordx4 v[246:247], off
	s_barrier
	s_waitcnt lgkmcnt(0)
	s_waitcnt lgkmcnt(0)
	v_mfma_f32_16x16x32_bf16 v[58:61], v[162:165], v[178:181], v[58:61]
	v_mfma_f32_16x16x32_bf16 v[50:53], v[170:173], v[178:181], v[50:53]
	v_mfma_f32_16x16x32_bf16 v[42:45], v[162:165], v[186:189], v[42:45]
	v_mfma_f32_16x16x32_bf16 v[34:37], v[170:173], v[186:189], v[34:37]
	v_mfma_f32_16x16x32_bf16 v[26:29], v[162:165], v[194:197], v[26:29]
	v_mfma_f32_16x16x32_bf16 v[18:21], v[170:173], v[194:197], v[18:21]
	v_mfma_f32_16x16x32_bf16 v[6:9], v[162:165], v[202:205], v[6:9]
	v_mfma_f32_16x16x32_bf16 v[2:5], v[170:173], v[202:205], v[2:5]
	v_mfma_f32_16x16x32_bf16 v[58:61], v[166:169], v[182:185], v[58:61]
	v_mfma_f32_16x16x32_bf16 v[50:53], v[174:177], v[182:185], v[50:53]
	v_mfma_f32_16x16x32_bf16 v[42:45], v[166:169], v[190:193], v[42:45]
	v_mfma_f32_16x16x32_bf16 v[34:37], v[174:177], v[190:193], v[34:37]
	v_mfma_f32_16x16x32_bf16 v[26:29], v[166:169], v[198:201], v[26:29]
	v_mfma_f32_16x16x32_bf16 v[18:21], v[174:177], v[198:201], v[18:21]
	v_mfma_f32_16x16x32_bf16 v[6:9], v[166:169], v[206:209], v[6:9]
	v_mfma_f32_16x16x32_bf16 v[2:5], v[174:177], v[206:209], v[2:5]
	s_barrier
	s_add_u32 s0, s0, s94
	s_addc_u32 s1, s1, 0
	s_add_i32 s7, s40, s3
	v_lshl_add_u64 v[248:249], s[0:1], 0, v[134:135]
	s_mov_b32 m0, s7
	v_lshl_add_u64 v[232:233], s[0:1], 0, v[130:131]
	global_load_lds_dwordx4 v[248:249], off
	s_add_i32 m0, s7, 0x2000
	s_nop 0
	global_load_lds_dwordx4 v[232:233], off
	s_waitcnt vmcnt(6)
	s_barrier
	v_mfma_f32_16x16x32_bf16 v[62:65], v[210:213], v[178:181], v[62:65]
	v_mfma_f32_16x16x32_bf16 v[54:57], v[238:241], v[178:181], v[54:57]
	v_mfma_f32_16x16x32_bf16 v[46:49], v[210:213], v[186:189], v[46:49]
	v_mfma_f32_16x16x32_bf16 v[38:41], v[238:241], v[186:189], v[38:41]
	v_mfma_f32_16x16x32_bf16 v[30:33], v[210:213], v[194:197], v[30:33]
	v_mfma_f32_16x16x32_bf16 v[22:25], v[238:241], v[194:197], v[22:25]
	v_mfma_f32_16x16x32_bf16 v[14:17], v[210:213], v[202:205], v[14:17]
	v_mfma_f32_16x16x32_bf16 v[10:13], v[238:241], v[202:205], v[10:13]
	v_mfma_f32_16x16x32_bf16 v[62:65], v[214:217], v[182:185], v[62:65]
	v_mfma_f32_16x16x32_bf16 v[54:57], v[242:245], v[182:185], v[54:57]
	v_mfma_f32_16x16x32_bf16 v[46:49], v[214:217], v[190:193], v[46:49]
	v_mfma_f32_16x16x32_bf16 v[38:41], v[242:245], v[190:193], v[38:41]
	v_mfma_f32_16x16x32_bf16 v[30:33], v[214:217], v[198:201], v[30:33]
	v_mfma_f32_16x16x32_bf16 v[22:25], v[242:245], v[198:201], v[22:25]
	v_mfma_f32_16x16x32_bf16 v[14:17], v[214:217], v[206:209], v[14:17]
	v_mfma_f32_16x16x32_bf16 v[10:13], v[242:245], v[206:209], v[10:13]
	s_add_i32 s0, 0, 0x18000
	v_add_u32_e32 v145, s0, v153
	s_barrier
	ds_read_b128 v[162:165], v145
	ds_read_b128 v[166:169], v145 offset:1024
	ds_read_b128 v[170:173], v145 offset:2048
	ds_read_b128 v[174:177], v145 offset:3072
	v_lshl_add_u64 v[150:151], v[150:151], 0, s[94:95]
	s_mov_b32 m0, s34
	v_lshl_add_u64 v[210:211], v[150:151], 0, v[136:137]
	ds_read_b128 v[178:181], v157 offset:32768
	ds_read_b128 v[182:185], v157 offset:33792
	ds_read_b128 v[186:189], v157 offset:34816
	ds_read_b128 v[190:193], v157 offset:35840
	ds_read_b128 v[194:197], v157 offset:36864
	ds_read_b128 v[198:201], v157 offset:37888
	ds_read_b128 v[202:205], v157 offset:38912
	ds_read_b128 v[206:209], v157 offset:39936
	global_load_lds_dwordx4 v[210:211], off
	v_lshl_add_u64 v[150:151], v[150:151], 0, v[132:133]
	s_mov_b32 m0, s35
	s_nop 0
	global_load_lds_dwordx4 v[150:151], off
	s_waitcnt lgkmcnt(8)
	s_barrier
	s_waitcnt lgkmcnt(0)
	s_waitcnt lgkmcnt(0)
	v_mfma_f32_16x16x32_bf16 v[126:129], v[162:165], v[178:181], v[126:129]
	v_mfma_f32_16x16x32_bf16 v[118:121], v[170:173], v[178:181], v[118:121]
	v_mfma_f32_16x16x32_bf16 v[110:113], v[162:165], v[186:189], v[110:113]
	v_mfma_f32_16x16x32_bf16 v[102:105], v[170:173], v[186:189], v[102:105]
	v_mfma_f32_16x16x32_bf16 v[94:97], v[162:165], v[194:197], v[94:97]
	v_mfma_f32_16x16x32_bf16 v[86:89], v[170:173], v[194:197], v[86:89]
	v_mfma_f32_16x16x32_bf16 v[78:81], v[162:165], v[202:205], v[78:81]
	v_mfma_f32_16x16x32_bf16 v[70:73], v[170:173], v[202:205], v[70:73]
	v_mfma_f32_16x16x32_bf16 v[126:129], v[166:169], v[182:185], v[126:129]
	v_mfma_f32_16x16x32_bf16 v[118:121], v[174:177], v[182:185], v[118:121]
	v_mfma_f32_16x16x32_bf16 v[110:113], v[166:169], v[190:193], v[110:113]
	v_mfma_f32_16x16x32_bf16 v[102:105], v[174:177], v[190:193], v[102:105]
	v_mfma_f32_16x16x32_bf16 v[94:97], v[166:169], v[198:201], v[94:97]
	v_mfma_f32_16x16x32_bf16 v[86:89], v[174:177], v[198:201], v[86:89]
	v_mfma_f32_16x16x32_bf16 v[78:81], v[166:169], v[206:209], v[78:81]
	v_mfma_f32_16x16x32_bf16 v[70:73], v[174:177], v[206:209], v[70:73]
	s_barrier
	s_add_i32 s1, 0, 0x1c000
	s_add_i32 s0, s0, s3
	v_add_u32_e32 v145, s1, v153
	v_lshl_add_u64 v[150:151], v[218:219], 0, s[84:85]
	s_mov_b32 m0, s0
	ds_read_b128 v[210:213], v145
	ds_read_b128 v[214:217], v145 offset:1024
	ds_read_b128 v[238:241], v145 offset:2048
	ds_read_b128 v[242:245], v145 offset:3072
	global_load_lds_dwordx4 v[150:151], off
	v_lshl_add_u64 v[150:151], v[224:225], 0, s[84:85]
	s_add_i32 m0, s0, 0x2000
	s_nop 0
	global_load_lds_dwordx4 v[150:151], off
	s_barrier
	s_waitcnt lgkmcnt(0)
	s_waitcnt lgkmcnt(0)
	v_mfma_f32_16x16x32_bf16 v[122:125], v[210:213], v[178:181], v[122:125]
	v_mfma_f32_16x16x32_bf16 v[114:117], v[238:241], v[178:181], v[114:117]
	v_mfma_f32_16x16x32_bf16 v[106:109], v[210:213], v[186:189], v[106:109]
	v_mfma_f32_16x16x32_bf16 v[98:101], v[238:241], v[186:189], v[98:101]
	v_mfma_f32_16x16x32_bf16 v[90:93], v[210:213], v[194:197], v[90:93]
	v_mfma_f32_16x16x32_bf16 v[82:85], v[238:241], v[194:197], v[82:85]
	v_mfma_f32_16x16x32_bf16 v[74:77], v[210:213], v[202:205], v[74:77]
	v_mfma_f32_16x16x32_bf16 v[66:69], v[238:241], v[202:205], v[66:69]
	v_mfma_f32_16x16x32_bf16 v[122:125], v[214:217], v[182:185], v[122:125]
	v_mfma_f32_16x16x32_bf16 v[114:117], v[242:245], v[182:185], v[114:117]
	v_mfma_f32_16x16x32_bf16 v[106:109], v[214:217], v[190:193], v[106:109]
	v_mfma_f32_16x16x32_bf16 v[98:101], v[242:245], v[190:193], v[98:101]
	v_mfma_f32_16x16x32_bf16 v[90:93], v[214:217], v[198:201], v[90:93]
	v_mfma_f32_16x16x32_bf16 v[82:85], v[242:245], v[198:201], v[82:85]
	v_mfma_f32_16x16x32_bf16 v[74:77], v[214:217], v[206:209], v[74:77]
	v_mfma_f32_16x16x32_bf16 v[66:69], v[242:245], v[206:209], v[66:69]
	s_mov_b32 m0, s36
	v_lshl_add_u64 v[150:151], v[230:231], 0, s[84:85]
	s_barrier
	ds_read_b128 v[178:181], v157 offset:49152
	ds_read_b128 v[182:185], v157 offset:50176
	ds_read_b128 v[186:189], v157 offset:51200
	ds_read_b128 v[190:193], v157 offset:52224
	ds_read_b128 v[194:197], v157 offset:53248
	ds_read_b128 v[198:201], v157 offset:54272
	ds_read_b128 v[202:205], v157 offset:55296
	ds_read_b128 v[206:209], v157 offset:56320
	global_load_lds_dwordx4 v[150:151], off
	v_lshl_add_u64 v[150:151], v[246:247], 0, s[84:85]
	s_mov_b32 m0, s42
	s_nop 0
	global_load_lds_dwordx4 v[150:151], off
	s_barrier
	s_waitcnt lgkmcnt(0)
	s_waitcnt lgkmcnt(0)
	v_mfma_f32_16x16x32_bf16 v[58:61], v[162:165], v[178:181], v[58:61]
	v_mfma_f32_16x16x32_bf16 v[50:53], v[170:173], v[178:181], v[50:53]
	v_mfma_f32_16x16x32_bf16 v[42:45], v[162:165], v[186:189], v[42:45]
	v_mfma_f32_16x16x32_bf16 v[34:37], v[170:173], v[186:189], v[34:37]
	v_mfma_f32_16x16x32_bf16 v[26:29], v[162:165], v[194:197], v[26:29]
	v_mfma_f32_16x16x32_bf16 v[18:21], v[170:173], v[194:197], v[18:21]
	v_mfma_f32_16x16x32_bf16 v[6:9], v[162:165], v[202:205], v[6:9]
	v_mfma_f32_16x16x32_bf16 v[2:5], v[170:173], v[202:205], v[2:5]
	v_mfma_f32_16x16x32_bf16 v[58:61], v[166:169], v[182:185], v[58:61]
	v_mfma_f32_16x16x32_bf16 v[50:53], v[174:177], v[182:185], v[50:53]
	v_mfma_f32_16x16x32_bf16 v[42:45], v[166:169], v[190:193], v[42:45]
	v_mfma_f32_16x16x32_bf16 v[34:37], v[174:177], v[190:193], v[34:37]
	v_mfma_f32_16x16x32_bf16 v[26:29], v[166:169], v[198:201], v[26:29]
	v_mfma_f32_16x16x32_bf16 v[18:21], v[174:177], v[198:201], v[18:21]
	v_mfma_f32_16x16x32_bf16 v[6:9], v[166:169], v[206:209], v[6:9]
	v_mfma_f32_16x16x32_bf16 v[2:5], v[174:177], v[206:209], v[2:5]
	s_barrier
	s_add_i32 s0, s1, s3
	v_lshl_add_u64 v[150:151], v[248:249], 0, s[84:85]
	s_mov_b32 m0, s0
	s_nop 0
	global_load_lds_dwordx4 v[150:151], off
	v_lshl_add_u64 v[150:151], v[232:233], 0, s[84:85]
	s_add_i32 m0, s0, 0x2000
	s_nop 0
	global_load_lds_dwordx4 v[150:151], off
	s_waitcnt vmcnt(6)
	s_barrier
	v_mfma_f32_16x16x32_bf16 v[62:65], v[210:213], v[178:181], v[62:65]
	v_mfma_f32_16x16x32_bf16 v[54:57], v[238:241], v[178:181], v[54:57]
	v_mfma_f32_16x16x32_bf16 v[46:49], v[210:213], v[186:189], v[46:49]
	v_mfma_f32_16x16x32_bf16 v[38:41], v[238:241], v[186:189], v[38:41]
	v_mfma_f32_16x16x32_bf16 v[30:33], v[210:213], v[194:197], v[30:33]
	v_mfma_f32_16x16x32_bf16 v[22:25], v[238:241], v[194:197], v[22:25]
	v_mfma_f32_16x16x32_bf16 v[14:17], v[210:213], v[202:205], v[14:17]
	v_mfma_f32_16x16x32_bf16 v[10:13], v[238:241], v[202:205], v[10:13]
	v_mfma_f32_16x16x32_bf16 v[62:65], v[214:217], v[182:185], v[62:65]
	v_mfma_f32_16x16x32_bf16 v[54:57], v[242:245], v[182:185], v[54:57]
	v_mfma_f32_16x16x32_bf16 v[46:49], v[214:217], v[190:193], v[46:49]
	v_mfma_f32_16x16x32_bf16 v[38:41], v[242:245], v[190:193], v[38:41]
	v_mfma_f32_16x16x32_bf16 v[30:33], v[214:217], v[198:201], v[30:33]
	v_mfma_f32_16x16x32_bf16 v[22:25], v[242:245], v[198:201], v[22:25]
	v_mfma_f32_16x16x32_bf16 v[14:17], v[214:217], v[206:209], v[14:17]
	v_mfma_f32_16x16x32_bf16 v[10:13], v[242:245], v[206:209], v[10:13]
	s_add_u32 s4, s4, 0x100
	s_addc_u32 s5, s5, 0
	v_lshl_add_u64 v[148:149], v[148:149], 0, s[86:87]
	s_cmp_ge_u32 s6, s13
	s_mov_b32 s0, s6
	s_barrier
	s_cbranch_scc0 .LBB0_824
	v_cmp_lt_i32_e32 vcc, v227, v222
	ds_read2st64_b32 v[150:151], v161 offset1:1
	ds_read2st64_b32 v[168:169], v161 offset0:2 offset1:3
	ds_read2st64_b32 v[170:171], v161 offset0:4 offset1:5
	ds_read2st64_b32 v[148:149], v161 offset0:6 offset1:7
	v_cndmask_b32_e32 v145, v221, v227, vcc
	v_cmp_lt_i32_e32 vcc, v228, v222
	s_mov_b32 s0, 0x358637bd
	v_lshlrev_b32_e32 v145, 2, v145
	s_mov_b32 s4, 0x3a800000
	v_lshl_or_b32 v164, s17, 7, v155
	v_cndmask_b32_e32 v224, v221, v228, vcc
	v_mov_b32_e32 v180, s0
	v_lshlrev_b32_e32 v224, 2, v224
	s_mov_b32 s17, s90
	s_mov_b32 s40, s91
	s_waitcnt lgkmcnt(0)
	ds_bpermute_b32 v172, v145, v150
	ds_bpermute_b32 v173, v145, v151
	ds_bpermute_b32 v174, v145, v168
	ds_bpermute_b32 v175, v145, v169
	ds_bpermute_b32 v176, v145, v170
	ds_bpermute_b32 v177, v145, v171
	ds_bpermute_b32 v178, v145, v148
	ds_bpermute_b32 v179, v145, v149
	v_ashrrev_i32_e32 v165, 31, v164
	v_mov_b64_e32 v[212:213], s[20:21]
	v_lshlrev_b64 v[216:217], 1, v[164:165]
	v_mad_i64_i32 v[212:213], vcc, v144, s89, v[212:213]
	s_waitcnt lgkmcnt(0)
	v_pk_add_f32 v[150:151], v[150:151], v[172:173]
	v_pk_add_f32 v[168:169], v[168:169], v[174:175]
	v_pk_add_f32 v[170:171], v[170:171], v[176:177]
	v_pk_add_f32 v[148:149], v[148:149], v[178:179]
	s_waitcnt lgkmcnt(0)
	ds_bpermute_b32 v172, v224, v150
	ds_bpermute_b32 v173, v224, v151
	ds_bpermute_b32 v174, v224, v168
	ds_bpermute_b32 v175, v224, v169
	ds_bpermute_b32 v176, v224, v170
	ds_bpermute_b32 v177, v224, v171
	ds_bpermute_b32 v178, v224, v148
	ds_bpermute_b32 v179, v224, v149
	v_mov_b64_e32 v[218:219], 0
	v_lshl_add_u64 v[212:213], v[212:213], 0, v[216:217]
	s_waitcnt lgkmcnt(0)
	v_pk_add_f32 v[150:151], v[150:151], v[172:173]
	v_pk_add_f32 v[168:169], v[168:169], v[174:175]
	v_pk_add_f32 v[170:171], v[170:171], v[176:177]
	v_pk_add_f32 v[148:149], v[148:149], v[178:179]
	v_pk_fma_f32 v[150:151], v[150:151], s[4:5], v[180:181] op_sel_hi:[1,0,0]
	v_pk_fma_f32 v[168:169], v[168:169], s[4:5], v[180:181] op_sel_hi:[1,0,0]
	v_pk_fma_f32 v[170:171], v[170:171], s[4:5], v[180:181] op_sel_hi:[1,0,0]
	v_pk_fma_f32 v[148:149], v[148:149], s[4:5], v[180:181] op_sel_hi:[1,0,0]
	s_mov_b32 s0, 0xbfb8aa3b
	v_rsq_f32_e32 v150, v150
	v_rsq_f32_e32 v151, v151
	v_rsq_f32_e32 v168, v168
	v_rsq_f32_e32 v169, v169
	v_rsq_f32_e32 v170, v170
	v_rsq_f32_e32 v171, v171
	v_rsq_f32_e32 v148, v148
	v_rsq_f32_e32 v149, v149
	v_pk_mul_f32 v[126:127], v[126:127], v[150:151] op_sel_hi:[1,0]
	v_pk_mul_f32 v[128:129], v[128:129], v[150:151] op_sel_hi:[1,0]
	v_pk_mul_f32 v[118:119], v[118:119], v[150:151] op_sel_hi:[1,0]
	v_pk_mul_f32 v[120:121], v[120:121], v[150:151] op_sel_hi:[1,0]
	v_pk_mul_f32 v[172:173], v[126:127], s[0:1] op_sel_hi:[1,0]
	v_pk_mul_f32 v[174:175], v[128:129], s[0:1] op_sel_hi:[1,0]
	v_pk_mul_f32 v[176:177], v[118:119], s[0:1] op_sel_hi:[1,0]
	v_pk_mul_f32 v[178:179], v[120:121], s[0:1] op_sel_hi:[1,0]
	v_pk_mul_f32 v[122:123], v[122:123], v[150:151] op_sel_hi:[1,0]
	v_pk_mul_f32 v[124:125], v[124:125], v[150:151] op_sel_hi:[1,0]
	v_pk_mul_f32 v[114:115], v[114:115], v[150:151] op_sel_hi:[1,0]
	v_pk_mul_f32 v[116:117], v[116:117], v[150:151] op_sel_hi:[1,0]
	v_exp_f32_e32 v172, v172
	v_pk_mul_f32 v[110:111], v[110:111], v[150:151] op_sel:[0,1] op_sel_hi:[1,1]
	v_pk_mul_f32 v[112:113], v[112:113], v[150:151] op_sel:[0,1] op_sel_hi:[1,1]
	v_exp_f32_e32 v173, v173
	v_pk_mul_f32 v[102:103], v[102:103], v[150:151] op_sel:[0,1] op_sel_hi:[1,1]
	v_exp_f32_e32 v174, v174
	v_pk_mul_f32 v[104:105], v[104:105], v[150:151] op_sel:[0,1] op_sel_hi:[1,1]
	v_pk_mul_f32 v[180:181], v[110:111], s[0:1] op_sel_hi:[1,0]
	v_exp_f32_e32 v175, v175
	v_pk_mul_f32 v[182:183], v[112:113], s[0:1] op_sel_hi:[1,0]
	v_exp_f32_e32 v176, v176
	v_pk_mul_f32 v[184:185], v[102:103], s[0:1] op_sel_hi:[1,0]
	v_pk_mul_f32 v[186:187], v[104:105], s[0:1] op_sel_hi:[1,0]
	v_exp_f32_e32 v177, v177
	v_pk_mul_f32 v[106:107], v[106:107], v[150:151] op_sel:[0,1] op_sel_hi:[1,1]
	v_exp_f32_e32 v178, v178
	v_pk_mul_f32 v[108:109], v[108:109], v[150:151] op_sel:[0,1] op_sel_hi:[1,1]
	v_pk_mul_f32 v[98:99], v[98:99], v[150:151] op_sel:[0,1] op_sel_hi:[1,1]
	v_exp_f32_e32 v179, v179
	v_pk_mul_f32 v[100:101], v[100:101], v[150:151] op_sel:[0,1] op_sel_hi:[1,1]
	v_exp_f32_e32 v180, v180
	v_pk_mul_f32 v[94:95], v[94:95], v[168:169] op_sel_hi:[1,0]
	v_pk_mul_f32 v[96:97], v[96:97], v[168:169] op_sel_hi:[1,0]
	v_exp_f32_e32 v181, v181
	v_pk_mul_f32 v[86:87], v[86:87], v[168:169] op_sel_hi:[1,0]
	v_pk_mul_f32 v[88:89], v[88:89], v[168:169] op_sel_hi:[1,0]
	v_exp_f32_e32 v182, v182
	v_pk_mul_f32 v[188:189], v[94:95], s[0:1] op_sel_hi:[1,0]
	v_pk_mul_f32 v[190:191], v[96:97], s[0:1] op_sel_hi:[1,0]
	v_exp_f32_e32 v183, v183
	v_pk_mul_f32 v[192:193], v[86:87], s[0:1] op_sel_hi:[1,0]
	v_pk_mul_f32 v[194:195], v[88:89], s[0:1] op_sel_hi:[1,0]
	v_exp_f32_e32 v184, v184
	v_pk_mul_f32 v[90:91], v[90:91], v[168:169] op_sel_hi:[1,0]
	v_pk_mul_f32 v[92:93], v[92:93], v[168:169] op_sel_hi:[1,0]
	v_exp_f32_e32 v185, v185
	v_pk_mul_f32 v[82:83], v[82:83], v[168:169] op_sel_hi:[1,0]
	v_pk_mul_f32 v[84:85], v[84:85], v[168:169] op_sel_hi:[1,0]
	v_exp_f32_e32 v186, v186
	v_pk_add_f32 v[172:173], v[172:173], 1.0 op_sel_hi:[1,0]
	v_pk_add_f32 v[174:175], v[174:175], 1.0 op_sel_hi:[1,0]
	v_exp_f32_e32 v187, v187
	v_pk_add_f32 v[176:177], v[176:177], 1.0 op_sel_hi:[1,0]
	v_pk_add_f32 v[178:179], v[178:179], 1.0 op_sel_hi:[1,0]
	v_exp_f32_e32 v188, v188
	v_pk_mul_f32 v[78:79], v[78:79], v[168:169] op_sel:[0,1] op_sel_hi:[1,1]
	v_rcp_f32_e32 v172, v172
	v_pk_mul_f32 v[80:81], v[80:81], v[168:169] op_sel:[0,1] op_sel_hi:[1,1]
	v_exp_f32_e32 v189, v189
	v_pk_mul_f32 v[70:71], v[70:71], v[168:169] op_sel:[0,1] op_sel_hi:[1,1]
	v_rcp_f32_e32 v173, v173
	v_pk_mul_f32 v[72:73], v[72:73], v[168:169] op_sel:[0,1] op_sel_hi:[1,1]
	v_exp_f32_e32 v190, v190
	v_pk_mul_f32 v[196:197], v[78:79], s[0:1] op_sel_hi:[1,0]
	v_rcp_f32_e32 v174, v174
	v_pk_mul_f32 v[198:199], v[80:81], s[0:1] op_sel_hi:[1,0]
	v_exp_f32_e32 v191, v191
	v_pk_mul_f32 v[200:201], v[70:71], s[0:1] op_sel_hi:[1,0]
	v_rcp_f32_e32 v175, v175
	v_pk_mul_f32 v[202:203], v[72:73], s[0:1] op_sel_hi:[1,0]
	v_exp_f32_e32 v192, v192
	v_pk_mul_f32 v[74:75], v[74:75], v[168:169] op_sel:[0,1] op_sel_hi:[1,1]
	v_rcp_f32_e32 v176, v176
	v_pk_mul_f32 v[76:77], v[76:77], v[168:169] op_sel:[0,1] op_sel_hi:[1,1]
	v_exp_f32_e32 v193, v193
	v_pk_mul_f32 v[66:67], v[66:67], v[168:169] op_sel:[0,1] op_sel_hi:[1,1]
	v_rcp_f32_e32 v177, v177
	v_pk_mul_f32 v[68:69], v[68:69], v[168:169] op_sel:[0,1] op_sel_hi:[1,1]
	v_exp_f32_e32 v194, v194
	v_pk_add_f32 v[180:181], v[180:181], 1.0 op_sel_hi:[1,0]
	v_rcp_f32_e32 v178, v178
	v_pk_add_f32 v[182:183], v[182:183], 1.0 op_sel_hi:[1,0]
	v_exp_f32_e32 v195, v195
	v_pk_add_f32 v[184:185], v[184:185], 1.0 op_sel_hi:[1,0]
	v_rcp_f32_e32 v179, v179
	v_pk_add_f32 v[186:187], v[186:187], 1.0 op_sel_hi:[1,0]
	v_exp_f32_e32 v196, v196
	v_pk_mul_f32 v[58:59], v[58:59], v[170:171] op_sel_hi:[1,0]
	v_pk_mul_f32 v[60:61], v[60:61], v[170:171] op_sel_hi:[1,0]
	v_rcp_f32_e32 v180, v180
	v_pk_mul_f32 v[50:51], v[50:51], v[170:171] op_sel_hi:[1,0]
	v_pk_mul_f32 v[52:53], v[52:53], v[170:171] op_sel_hi:[1,0]
	v_exp_f32_e32 v197, v197
	v_pk_mul_f32 v[204:205], v[58:59], s[0:1] op_sel_hi:[1,0]
	v_pk_mul_f32 v[206:207], v[60:61], s[0:1] op_sel_hi:[1,0]
	v_rcp_f32_e32 v181, v181
	v_pk_mul_f32 v[208:209], v[50:51], s[0:1] op_sel_hi:[1,0]
	v_pk_mul_f32 v[210:211], v[52:53], s[0:1] op_sel_hi:[1,0]
	v_exp_f32_e32 v198, v198
	v_pk_mul_f32 v[62:63], v[62:63], v[170:171] op_sel_hi:[1,0]
	v_pk_mul_f32 v[64:65], v[64:65], v[170:171] op_sel_hi:[1,0]
	v_rcp_f32_e32 v182, v182
	v_pk_mul_f32 v[54:55], v[54:55], v[170:171] op_sel_hi:[1,0]
	v_exp_f32_e32 v199, v199
	v_pk_mul_f32 v[56:57], v[56:57], v[170:171] op_sel_hi:[1,0]
	v_pk_add_f32 v[188:189], v[188:189], 1.0 op_sel_hi:[1,0]
	v_rcp_f32_e32 v183, v183
	v_pk_add_f32 v[190:191], v[190:191], 1.0 op_sel_hi:[1,0]
	v_pk_add_f32 v[192:193], v[192:193], 1.0 op_sel_hi:[1,0]
	v_exp_f32_e32 v200, v200
	v_pk_add_f32 v[194:195], v[194:195], 1.0 op_sel_hi:[1,0]
	v_pk_mul_f32 v[126:127], v[126:127], v[172:173]
	v_rcp_f32_e32 v184, v184
	v_pk_mul_f32 v[128:129], v[128:129], v[174:175]
	v_pk_mul_f32 v[118:119], v[118:119], v[176:177]
	v_exp_f32_e32 v201, v201
	v_pk_mul_f32 v[120:121], v[120:121], v[178:179]
	v_rcp_f32_e32 v185, v185
	v_pk_mul_f32 v[122:123], v[122:123], v[126:127]
	v_pk_mul_f32 v[124:125], v[124:125], v[128:129]
	v_exp_f32_e32 v202, v202
	v_pk_mul_f32 v[114:115], v[114:115], v[118:119]
	v_pk_mul_f32 v[116:117], v[116:117], v[120:121]
	v_rcp_f32_e32 v186, v186
	v_cvt_pk_bf16_f32 v122, v122, v123
	v_cvt_pk_bf16_f32 v123, v124, v125
	v_exp_f32_e32 v203, v203
	v_cvt_pk_bf16_f32 v124, v114, v115
	v_cvt_pk_bf16_f32 v125, v116, v117
	v_rcp_f32_e32 v187, v187
	global_store_dwordx4 v[212:213], v[122:125], off
	v_exp_f32_e32 v204, v204
	v_pk_mul_f32 v[42:43], v[42:43], v[170:171] op_sel:[0,1] op_sel_hi:[1,1]
	v_pk_mul_f32 v[44:45], v[44:45], v[170:171] op_sel:[0,1] op_sel_hi:[1,1]
	v_rcp_f32_e32 v188, v188
	v_pk_mul_f32 v[34:35], v[34:35], v[170:171] op_sel:[0,1] op_sel_hi:[1,1]
	v_pk_mul_f32 v[36:37], v[36:37], v[170:171] op_sel:[0,1] op_sel_hi:[1,1]
	v_exp_f32_e32 v205, v205
	v_pk_mul_f32 v[172:173], v[42:43], s[0:1] op_sel_hi:[1,0]
	v_pk_mul_f32 v[174:175], v[44:45], s[0:1] op_sel_hi:[1,0]
	v_rcp_f32_e32 v189, v189
	v_pk_mul_f32 v[176:177], v[34:35], s[0:1] op_sel_hi:[1,0]
	v_pk_mul_f32 v[178:179], v[36:37], s[0:1] op_sel_hi:[1,0]
	v_exp_f32_e32 v206, v206
	v_pk_mul_f32 v[46:47], v[46:47], v[170:171] op_sel:[0,1] op_sel_hi:[1,1]
	v_pk_mul_f32 v[48:49], v[48:49], v[170:171] op_sel:[0,1] op_sel_hi:[1,1]
	v_rcp_f32_e32 v190, v190
	v_pk_mul_f32 v[38:39], v[38:39], v[170:171] op_sel:[0,1] op_sel_hi:[1,1]
	v_pk_mul_f32 v[40:41], v[40:41], v[170:171] op_sel:[0,1] op_sel_hi:[1,1]
	v_exp_f32_e32 v207, v207
	v_pk_add_f32 v[196:197], v[196:197], 1.0 op_sel_hi:[1,0]
	v_pk_add_f32 v[198:199], v[198:199], 1.0 op_sel_hi:[1,0]
	v_rcp_f32_e32 v191, v191
	v_pk_add_f32 v[200:201], v[200:201], 1.0 op_sel_hi:[1,0]
	v_pk_add_f32 v[202:203], v[202:203], 1.0 op_sel_hi:[1,0]
	v_exp_f32_e32 v208, v208
	v_pk_mul_f32 v[110:111], v[110:111], v[180:181]
	v_pk_mul_f32 v[112:113], v[112:113], v[182:183]
	v_rcp_f32_e32 v192, v192
	v_pk_mul_f32 v[102:103], v[102:103], v[184:185]
	v_pk_mul_f32 v[104:105], v[104:105], v[186:187]
	v_exp_f32_e32 v209, v209
	s_mov_b32 s4, 0x16000
	s_mov_b32 s5, 0
	v_rcp_f32_e32 v193, v193
	v_pk_mul_f32 v[106:107], v[106:107], v[110:111]
	v_pk_mul_f32 v[108:109], v[108:109], v[112:113]
	v_exp_f32_e32 v210, v210
	v_lshl_add_u64 v[214:215], v[212:213], 0, s[4:5]
	v_pk_mul_f32 v[98:99], v[98:99], v[102:103]
	v_rcp_f32_e32 v194, v194
	v_pk_mul_f32 v[100:101], v[100:101], v[104:105]
	v_cvt_pk_bf16_f32 v106, v106, v107
	v_exp_f32_e32 v211, v211
	v_cvt_pk_bf16_f32 v107, v108, v109
	v_cvt_pk_bf16_f32 v108, v98, v99
	v_rcp_f32_e32 v195, v195
	v_cvt_pk_bf16_f32 v109, v100, v101
	global_store_dwordx4 v[214:215], v[106:109], off
	v_exp_f32_e32 v172, v172
	v_pk_mul_f32 v[26:27], v[26:27], v[148:149] op_sel_hi:[1,0]
	v_pk_mul_f32 v[28:29], v[28:29], v[148:149] op_sel_hi:[1,0]
	v_rcp_f32_e32 v196, v196
	v_pk_mul_f32 v[18:19], v[18:19], v[148:149] op_sel_hi:[1,0]
	v_pk_mul_f32 v[20:21], v[20:21], v[148:149] op_sel_hi:[1,0]
	v_exp_f32_e32 v173, v173
	v_pk_mul_f32 v[180:181], v[26:27], s[0:1] op_sel_hi:[1,0]
	v_pk_mul_f32 v[182:183], v[28:29], s[0:1] op_sel_hi:[1,0]
	v_rcp_f32_e32 v197, v197
	v_pk_mul_f32 v[184:185], v[18:19], s[0:1] op_sel_hi:[1,0]
	v_pk_mul_f32 v[186:187], v[20:21], s[0:1] op_sel_hi:[1,0]
	v_exp_f32_e32 v174, v174
	v_pk_mul_f32 v[30:31], v[30:31], v[148:149] op_sel_hi:[1,0]
	v_pk_mul_f32 v[32:33], v[32:33], v[148:149] op_sel_hi:[1,0]
	v_rcp_f32_e32 v198, v198
	v_pk_mul_f32 v[22:23], v[22:23], v[148:149] op_sel_hi:[1,0]
	v_pk_mul_f32 v[24:25], v[24:25], v[148:149] op_sel_hi:[1,0]
	v_exp_f32_e32 v175, v175
	v_pk_add_f32 v[204:205], v[204:205], 1.0 op_sel_hi:[1,0]
	v_pk_add_f32 v[206:207], v[206:207], 1.0 op_sel_hi:[1,0]
	v_rcp_f32_e32 v199, v199
	v_pk_add_f32 v[208:209], v[208:209], 1.0 op_sel_hi:[1,0]
	v_pk_add_f32 v[210:211], v[210:211], 1.0 op_sel_hi:[1,0]
	v_exp_f32_e32 v176, v176
	v_pk_mul_f32 v[94:95], v[94:95], v[188:189]
	v_pk_mul_f32 v[96:97], v[96:97], v[190:191]
	v_rcp_f32_e32 v200, v200
	v_pk_mul_f32 v[86:87], v[86:87], v[192:193]
	v_pk_mul_f32 v[88:89], v[88:89], v[194:195]
	v_exp_f32_e32 v177, v177
	s_mov_b32 s4, 0x16000
	s_mov_b32 s5, 0
	v_rcp_f32_e32 v201, v201
	v_pk_mul_f32 v[90:91], v[90:91], v[94:95]
	v_pk_mul_f32 v[92:93], v[92:93], v[96:97]
	v_exp_f32_e32 v178, v178
	v_lshl_add_u64 v[212:213], v[214:215], 0, s[4:5]
	v_pk_mul_f32 v[82:83], v[82:83], v[86:87]
	v_rcp_f32_e32 v202, v202
	v_pk_mul_f32 v[84:85], v[84:85], v[88:89]
	v_cvt_pk_bf16_f32 v90, v90, v91
	v_exp_f32_e32 v179, v179
	v_cvt_pk_bf16_f32 v91, v92, v93
	v_cvt_pk_bf16_f32 v92, v82, v83
	v_rcp_f32_e32 v203, v203
	v_cvt_pk_bf16_f32 v93, v84, v85
	global_store_dwordx4 v[212:213], v[90:93], off
	v_exp_f32_e32 v180, v180
	v_pk_mul_f32 v[6:7], v[6:7], v[148:149] op_sel:[0,1] op_sel_hi:[1,1]
	v_pk_mul_f32 v[8:9], v[8:9], v[148:149] op_sel:[0,1] op_sel_hi:[1,1]
	v_rcp_f32_e32 v204, v204
	v_pk_mul_f32 v[2:3], v[2:3], v[148:149] op_sel:[0,1] op_sel_hi:[1,1]
	v_pk_mul_f32 v[4:5], v[4:5], v[148:149] op_sel:[0,1] op_sel_hi:[1,1]
	v_exp_f32_e32 v181, v181
	v_pk_mul_f32 v[188:189], v[6:7], s[0:1] op_sel_hi:[1,0]
	v_pk_mul_f32 v[190:191], v[8:9], s[0:1] op_sel_hi:[1,0]
	v_rcp_f32_e32 v205, v205
	v_pk_mul_f32 v[192:193], v[2:3], s[0:1] op_sel_hi:[1,0]
	v_pk_mul_f32 v[194:195], v[4:5], s[0:1] op_sel_hi:[1,0]
	v_exp_f32_e32 v182, v182
	v_pk_mul_f32 v[14:15], v[14:15], v[148:149] op_sel:[0,1] op_sel_hi:[1,1]
	v_pk_mul_f32 v[16:17], v[16:17], v[148:149] op_sel:[0,1] op_sel_hi:[1,1]
	v_rcp_f32_e32 v206, v206
	v_pk_mul_f32 v[10:11], v[10:11], v[148:149] op_sel:[0,1] op_sel_hi:[1,1]
	v_pk_mul_f32 v[12:13], v[12:13], v[148:149] op_sel:[0,1] op_sel_hi:[1,1]
	v_exp_f32_e32 v183, v183
	v_pk_add_f32 v[172:173], v[172:173], 1.0 op_sel_hi:[1,0]
	v_pk_add_f32 v[174:175], v[174:175], 1.0 op_sel_hi:[1,0]
	v_rcp_f32_e32 v207, v207
	v_pk_add_f32 v[176:177], v[176:177], 1.0 op_sel_hi:[1,0]
	v_pk_add_f32 v[178:179], v[178:179], 1.0 op_sel_hi:[1,0]
	v_exp_f32_e32 v184, v184
	v_pk_mul_f32 v[78:79], v[78:79], v[196:197]
	v_pk_mul_f32 v[80:81], v[80:81], v[198:199]
	v_rcp_f32_e32 v208, v208
	v_pk_mul_f32 v[70:71], v[70:71], v[200:201]
	v_pk_mul_f32 v[72:73], v[72:73], v[202:203]
	v_exp_f32_e32 v185, v185
	s_mov_b32 s4, 0x16000
	s_mov_b32 s5, 0
	v_rcp_f32_e32 v209, v209
	v_pk_mul_f32 v[74:75], v[74:75], v[78:79]
	v_pk_mul_f32 v[76:77], v[76:77], v[80:81]
	v_exp_f32_e32 v186, v186
	v_lshl_add_u64 v[214:215], v[212:213], 0, s[4:5]
	v_pk_mul_f32 v[66:67], v[66:67], v[70:71]
	v_rcp_f32_e32 v210, v210
	v_pk_mul_f32 v[68:69], v[68:69], v[72:73]
	v_cvt_pk_bf16_f32 v74, v74, v75
	v_exp_f32_e32 v187, v187
	v_cvt_pk_bf16_f32 v75, v76, v77
	v_cvt_pk_bf16_f32 v76, v66, v67
	v_rcp_f32_e32 v211, v211
	v_cvt_pk_bf16_f32 v77, v68, v69
	global_store_dwordx4 v[214:215], v[74:77], off
	v_exp_f32_e32 v188, v188
	v_pk_add_f32 v[180:181], v[180:181], 1.0 op_sel_hi:[1,0]
	v_pk_add_f32 v[182:183], v[182:183], 1.0 op_sel_hi:[1,0]
	v_rcp_f32_e32 v172, v172
	v_pk_add_f32 v[184:185], v[184:185], 1.0 op_sel_hi:[1,0]
	v_exp_f32_e32 v189, v189
	v_pk_add_f32 v[186:187], v[186:187], 1.0 op_sel_hi:[1,0]
	v_rcp_f32_e32 v173, v173
	v_pk_mul_f32 v[58:59], v[58:59], v[204:205]
	v_exp_f32_e32 v190, v190
	v_pk_mul_f32 v[60:61], v[60:61], v[206:207]
	v_pk_mul_f32 v[50:51], v[50:51], v[208:209]
	v_rcp_f32_e32 v174, v174
	v_pk_mul_f32 v[52:53], v[52:53], v[210:211]
	v_exp_f32_e32 v191, v191
	s_mov_b32 s4, 0x6e000
	v_rcp_f32_e32 v175, v175
	s_mov_b32 s5, 0
	v_exp_f32_e32 v192, v192
	v_pk_mul_f32 v[62:63], v[62:63], v[58:59]
	v_pk_mul_f32 v[64:65], v[64:65], v[60:61]
	v_rcp_f32_e32 v176, v176
	v_lshl_add_u64 v[212:213], v[214:215], 0, s[4:5]
	v_exp_f32_e32 v193, v193
	v_pk_mul_f32 v[54:55], v[54:55], v[50:51]
	v_rcp_f32_e32 v177, v177
	v_pk_mul_f32 v[56:57], v[56:57], v[52:53]
	v_exp_f32_e32 v194, v194
	v_cvt_pk_bf16_f32 v62, v62, v63
	v_cvt_pk_bf16_f32 v63, v64, v65
	v_rcp_f32_e32 v178, v178
	v_cvt_pk_bf16_f32 v64, v54, v55
	v_exp_f32_e32 v195, v195
	v_cvt_pk_bf16_f32 v65, v56, v57
	v_rcp_f32_e32 v179, v179
	global_store_dwordx4 v[212:213], v[62:65], off
	v_rcp_f32_e32 v180, v180
	v_pk_add_f32 v[188:189], v[188:189], 1.0 op_sel_hi:[1,0]
	v_pk_add_f32 v[190:191], v[190:191], 1.0 op_sel_hi:[1,0]
	v_pk_add_f32 v[192:193], v[192:193], 1.0 op_sel_hi:[1,0]
	v_rcp_f32_e32 v181, v181
	v_pk_add_f32 v[194:195], v[194:195], 1.0 op_sel_hi:[1,0]
	v_pk_mul_f32 v[42:43], v[42:43], v[172:173]
	v_rcp_f32_e32 v182, v182
	v_pk_mul_f32 v[44:45], v[44:45], v[174:175]
	v_pk_mul_f32 v[34:35], v[34:35], v[176:177]
	v_pk_mul_f32 v[36:37], v[36:37], v[178:179]
	v_rcp_f32_e32 v183, v183
	s_mov_b32 s4, 0x16000
	s_mov_b32 s5, 0
	v_rcp_f32_e32 v184, v184
	v_pk_mul_f32 v[46:47], v[46:47], v[42:43]
	v_pk_mul_f32 v[48:49], v[48:49], v[44:45]
	v_lshl_add_u64 v[214:215], v[212:213], 0, s[4:5]
	v_rcp_f32_e32 v185, v185
	v_pk_mul_f32 v[38:39], v[38:39], v[34:35]
	v_pk_mul_f32 v[40:41], v[40:41], v[36:37]
	v_rcp_f32_e32 v186, v186
	v_cvt_pk_bf16_f32 v46, v46, v47
	v_cvt_pk_bf16_f32 v47, v48, v49
	v_cvt_pk_bf16_f32 v48, v38, v39
	v_rcp_f32_e32 v187, v187
	v_cvt_pk_bf16_f32 v49, v40, v41
	global_store_dwordx4 v[214:215], v[46:49], off
	v_rcp_f32_e32 v188, v188
	v_pk_mul_f32 v[26:27], v[26:27], v[180:181]
	v_pk_mul_f32 v[28:29], v[28:29], v[182:183]
	v_rcp_f32_e32 v189, v189
	v_pk_mul_f32 v[18:19], v[18:19], v[184:185]
	v_pk_mul_f32 v[20:21], v[20:21], v[186:187]
	v_rcp_f32_e32 v190, v190
	s_mov_b32 s4, 0x16000
	s_mov_b32 s5, 0
	v_rcp_f32_e32 v191, v191
	v_pk_mul_f32 v[30:31], v[30:31], v[26:27]
	v_pk_mul_f32 v[32:33], v[32:33], v[28:29]
	v_rcp_f32_e32 v192, v192
	v_lshl_add_u64 v[212:213], v[214:215], 0, s[4:5]
	v_pk_mul_f32 v[22:23], v[22:23], v[18:19]
	v_rcp_f32_e32 v193, v193
	v_pk_mul_f32 v[24:25], v[24:25], v[20:21]
	v_cvt_pk_bf16_f32 v30, v30, v31
	v_rcp_f32_e32 v194, v194
	v_cvt_pk_bf16_f32 v31, v32, v33
	v_cvt_pk_bf16_f32 v32, v22, v23
	v_rcp_f32_e32 v195, v195
	v_cvt_pk_bf16_f32 v33, v24, v25
	global_store_dwordx4 v[212:213], v[30:33], off
	v_pk_mul_f32 v[6:7], v[6:7], v[188:189]
	v_pk_mul_f32 v[8:9], v[8:9], v[190:191]
	v_pk_mul_f32 v[2:3], v[2:3], v[192:193]
	v_pk_mul_f32 v[4:5], v[4:5], v[194:195]
	s_mov_b32 s4, 0x16000
	s_mov_b32 s5, 0
	v_pk_mul_f32 v[14:15], v[14:15], v[6:7]
	v_pk_mul_f32 v[16:17], v[16:17], v[8:9]
	v_lshl_add_u64 v[214:215], v[212:213], 0, s[4:5]
	v_pk_mul_f32 v[10:11], v[10:11], v[2:3]
	v_pk_mul_f32 v[12:13], v[12:13], v[4:5]
	v_cvt_pk_bf16_f32 v14, v14, v15
	v_cvt_pk_bf16_f32 v15, v16, v17
	v_cvt_pk_bf16_f32 v16, v10, v11
	v_cvt_pk_bf16_f32 v17, v12, v13
	global_store_dwordx4 v[214:215], v[14:17], off
	v_mov_b64_e32 v[2:3], v[146:147]
	s_mov_b64 s[4:5], s[22:23]
	s_and_b64 vcc, exec, s[38:39]
	s_cbranch_vccz .LBB0_815
	s_waitcnt vmcnt(0)
	s_cmpk_gt_u32 s2, 0xff
	v_readlane_b32 s89, v253, 39
	s_cbranch_scc1 .LBB0_14
	s_barrier
	s_branch .LBB0_14
